# conv LN reduction via permlane32/16 swap transpose-reduce + 32 DPP adds (instead of 192 DPP); rest as previous
# baseline (speedup 1.0000x reference)
; __device__ __forceinline__ void p3_conv(const Ptrs& P, LAS unsigned char* lds, int first, int stride, int tid, int wave, int lane) {
;     ...
;         f32x2 a[16];
; #pragma unroll
;         for (int t = 0; t < 16; ++t) a[t] = cb;
; #pragma unroll
;         for (int r = 0; r < 46; ++r) {
;             const f32x2 u = (f32x2){bflo(uv[r]), bfhi(uv[r])};
; #pragma unroll
;             for (int t = 0; t < 16; ++t) { const int k = r - t; if (k >= 0 && k < CONV_W) a[t] += u * w[k]; }
;         }
.Lcv_nomask:
	v_lshlrev_b32_e32 v236, 16, v102
	v_and_b32_e32 v237, 0xffff0000, v102
	v_pk_fma_f32 v[204:205], v[2:3], v[236:237], v[64:65]
	v_lshlrev_b32_e32 v238, 16, v103
	v_and_b32_e32 v239, 0xffff0000, v103
	v_pk_fma_f32 v[204:205], v[4:5], v[238:239], v[204:205]
	v_pk_fma_f32 v[206:207], v[2:3], v[238:239], v[64:65]
	v_lshlrev_b32_e32 v240, 16, v100
	v_and_b32_e32 v241, 0xffff0000, v100
	v_pk_fma_f32 v[204:205], v[6:7], v[240:241], v[204:205]
	v_pk_fma_f32 v[206:207], v[4:5], v[240:241], v[206:207]
	v_pk_fma_f32 v[208:209], v[2:3], v[240:241], v[64:65]
	v_lshlrev_b32_e32 v236, 16, v101
	v_and_b32_e32 v237, 0xffff0000, v101
	v_pk_fma_f32 v[204:205], v[8:9], v[236:237], v[204:205]
	v_pk_fma_f32 v[206:207], v[6:7], v[236:237], v[206:207]
	v_pk_fma_f32 v[208:209], v[4:5], v[236:237], v[208:209]
	v_pk_fma_f32 v[210:211], v[2:3], v[236:237], v[64:65]
	v_lshlrev_b32_e32 v238, 16, v98
	v_and_b32_e32 v239, 0xffff0000, v98
	v_pk_fma_f32 v[204:205], v[10:11], v[238:239], v[204:205]
	v_pk_fma_f32 v[206:207], v[8:9], v[238:239], v[206:207]
	v_pk_fma_f32 v[208:209], v[6:7], v[238:239], v[208:209]
	v_pk_fma_f32 v[210:211], v[4:5], v[238:239], v[210:211]
	v_pk_fma_f32 v[212:213], v[2:3], v[238:239], v[64:65]
	v_lshlrev_b32_e32 v240, 16, v99
	v_and_b32_e32 v241, 0xffff0000, v99
	v_pk_fma_f32 v[204:205], v[12:13], v[240:241], v[204:205]
	v_pk_fma_f32 v[206:207], v[10:11], v[240:241], v[206:207]
	v_pk_fma_f32 v[208:209], v[8:9], v[240:241], v[208:209]
	v_pk_fma_f32 v[210:211], v[6:7], v[240:241], v[210:211]
	v_pk_fma_f32 v[212:213], v[4:5], v[240:241], v[212:213]
	v_pk_fma_f32 v[214:215], v[2:3], v[240:241], v[64:65]
	v_lshlrev_b32_e32 v236, 16, v96
	v_and_b32_e32 v237, 0xffff0000, v96
	v_pk_fma_f32 v[204:205], v[14:15], v[236:237], v[204:205]
	v_pk_fma_f32 v[206:207], v[12:13], v[236:237], v[206:207]
	v_pk_fma_f32 v[208:209], v[10:11], v[236:237], v[208:209]
	v_pk_fma_f32 v[210:211], v[8:9], v[236:237], v[210:211]
	v_pk_fma_f32 v[212:213], v[6:7], v[236:237], v[212:213]
	v_pk_fma_f32 v[214:215], v[4:5], v[236:237], v[214:215]
	v_pk_fma_f32 v[216:217], v[2:3], v[236:237], v[64:65]
	v_lshlrev_b32_e32 v238, 16, v97
	v_and_b32_e32 v239, 0xffff0000, v97
	v_pk_fma_f32 v[204:205], v[16:17], v[238:239], v[204:205]
	v_pk_fma_f32 v[206:207], v[14:15], v[238:239], v[206:207]
	v_pk_fma_f32 v[208:209], v[12:13], v[238:239], v[208:209]
	v_pk_fma_f32 v[210:211], v[10:11], v[238:239], v[210:211]
	v_pk_fma_f32 v[212:213], v[8:9], v[238:239], v[212:213]
	v_pk_fma_f32 v[214:215], v[6:7], v[238:239], v[214:215]
	v_pk_fma_f32 v[216:217], v[4:5], v[238:239], v[216:217]
	v_pk_fma_f32 v[218:219], v[2:3], v[238:239], v[64:65]
	v_lshlrev_b32_e32 v240, 16, v94
	v_and_b32_e32 v241, 0xffff0000, v94
	v_pk_fma_f32 v[204:205], v[18:19], v[240:241], v[204:205]
	v_pk_fma_f32 v[206:207], v[16:17], v[240:241], v[206:207]
	v_pk_fma_f32 v[208:209], v[14:15], v[240:241], v[208:209]
	v_pk_fma_f32 v[210:211], v[12:13], v[240:241], v[210:211]
	v_pk_fma_f32 v[212:213], v[10:11], v[240:241], v[212:213]
	v_pk_fma_f32 v[214:215], v[8:9], v[240:241], v[214:215]
	v_pk_fma_f32 v[216:217], v[6:7], v[240:241], v[216:217]
	v_pk_fma_f32 v[218:219], v[4:5], v[240:241], v[218:219]
	v_pk_fma_f32 v[220:221], v[2:3], v[240:241], v[64:65]
	v_lshlrev_b32_e32 v236, 16, v95
	v_and_b32_e32 v237, 0xffff0000, v95
	v_pk_fma_f32 v[204:205], v[20:21], v[236:237], v[204:205]
	v_pk_fma_f32 v[206:207], v[18:19], v[236:237], v[206:207]
	v_pk_fma_f32 v[208:209], v[16:17], v[236:237], v[208:209]
	v_pk_fma_f32 v[210:211], v[14:15], v[236:237], v[210:211]
	v_pk_fma_f32 v[212:213], v[12:13], v[236:237], v[212:213]
	v_pk_fma_f32 v[214:215], v[10:11], v[236:237], v[214:215]
	v_pk_fma_f32 v[216:217], v[8:9], v[236:237], v[216:217]
	v_pk_fma_f32 v[218:219], v[6:7], v[236:237], v[218:219]
	v_pk_fma_f32 v[220:221], v[4:5], v[236:237], v[220:221]
	v_pk_fma_f32 v[222:223], v[2:3], v[236:237], v[64:65]
	v_lshlrev_b32_e32 v238, 16, v92
	v_and_b32_e32 v239, 0xffff0000, v92
	v_pk_fma_f32 v[204:205], v[22:23], v[238:239], v[204:205]
	v_pk_fma_f32 v[206:207], v[20:21], v[238:239], v[206:207]
	v_pk_fma_f32 v[208:209], v[18:19], v[238:239], v[208:209]
	v_pk_fma_f32 v[210:211], v[16:17], v[238:239], v[210:211]
	v_pk_fma_f32 v[212:213], v[14:15], v[238:239], v[212:213]
	v_pk_fma_f32 v[214:215], v[12:13], v[238:239], v[214:215]
	v_pk_fma_f32 v[216:217], v[10:11], v[238:239], v[216:217]
	v_pk_fma_f32 v[218:219], v[8:9], v[238:239], v[218:219]
	v_pk_fma_f32 v[220:221], v[6:7], v[238:239], v[220:221]
	v_pk_fma_f32 v[222:223], v[4:5], v[238:239], v[222:223]
	v_pk_fma_f32 v[224:225], v[2:3], v[238:239], v[64:65]
	v_lshlrev_b32_e32 v240, 16, v93
	v_and_b32_e32 v241, 0xffff0000, v93
	v_pk_fma_f32 v[204:205], v[24:25], v[240:241], v[204:205]
	v_pk_fma_f32 v[206:207], v[22:23], v[240:241], v[206:207]
	v_pk_fma_f32 v[208:209], v[20:21], v[240:241], v[208:209]
	v_pk_fma_f32 v[210:211], v[18:19], v[240:241], v[210:211]
	v_pk_fma_f32 v[212:213], v[16:17], v[240:241], v[212:213]
	v_pk_fma_f32 v[214:215], v[14:15], v[240:241], v[214:215]
	v_pk_fma_f32 v[216:217], v[12:13], v[240:241], v[216:217]
	v_pk_fma_f32 v[218:219], v[10:11], v[240:241], v[218:219]
	v_pk_fma_f32 v[220:221], v[8:9], v[240:241], v[220:221]
	v_pk_fma_f32 v[222:223], v[6:7], v[240:241], v[222:223]
	v_pk_fma_f32 v[224:225], v[4:5], v[240:241], v[224:225]
	v_pk_fma_f32 v[226:227], v[2:3], v[240:241], v[64:65]
	v_lshlrev_b32_e32 v236, 16, v90
	v_and_b32_e32 v237, 0xffff0000, v90
	v_pk_fma_f32 v[204:205], v[26:27], v[236:237], v[204:205]
	v_pk_fma_f32 v[206:207], v[24:25], v[236:237], v[206:207]
	v_pk_fma_f32 v[208:209], v[22:23], v[236:237], v[208:209]
	v_pk_fma_f32 v[210:211], v[20:21], v[236:237], v[210:211]
; __device__ __forceinline__ void p3_conv(const Ptrs& P, LAS unsigned char* lds, int first, int stride, int tid, int wave, int lane) {
;     ...
;         for (int r = 0; r < 46; ++r) {
;             const f32x2 u = (f32x2){bflo(uv[r]), bfhi(uv[r])};
; #pragma unroll
;             for (int t = 0; t < 16; ++t) { const int k = r - t; if (k >= 0 && k < CONV_W) a[t] += u * w[k]; }
;         }
	v_pk_fma_f32 v[212:213], v[18:19], v[236:237], v[212:213]
	v_pk_fma_f32 v[214:215], v[16:17], v[236:237], v[214:215]
	v_pk_fma_f32 v[216:217], v[14:15], v[236:237], v[216:217]
	v_pk_fma_f32 v[218:219], v[12:13], v[236:237], v[218:219]
	v_pk_fma_f32 v[220:221], v[10:11], v[236:237], v[220:221]
	v_pk_fma_f32 v[222:223], v[8:9], v[236:237], v[222:223]
	v_pk_fma_f32 v[224:225], v[6:7], v[236:237], v[224:225]
	v_pk_fma_f32 v[226:227], v[4:5], v[236:237], v[226:227]
	v_pk_fma_f32 v[228:229], v[2:3], v[236:237], v[64:65]
	v_lshlrev_b32_e32 v238, 16, v91
	v_and_b32_e32 v239, 0xffff0000, v91
	v_pk_fma_f32 v[204:205], v[28:29], v[238:239], v[204:205]
	v_pk_fma_f32 v[206:207], v[26:27], v[238:239], v[206:207]
	v_pk_fma_f32 v[208:209], v[24:25], v[238:239], v[208:209]
	v_pk_fma_f32 v[210:211], v[22:23], v[238:239], v[210:211]
	v_pk_fma_f32 v[212:213], v[20:21], v[238:239], v[212:213]
	v_pk_fma_f32 v[214:215], v[18:19], v[238:239], v[214:215]
	v_pk_fma_f32 v[216:217], v[16:17], v[238:239], v[216:217]
	v_pk_fma_f32 v[218:219], v[14:15], v[238:239], v[218:219]
	v_pk_fma_f32 v[220:221], v[12:13], v[238:239], v[220:221]
	v_pk_fma_f32 v[222:223], v[10:11], v[238:239], v[222:223]
	v_pk_fma_f32 v[224:225], v[8:9], v[238:239], v[224:225]
	v_pk_fma_f32 v[226:227], v[6:7], v[238:239], v[226:227]
	v_pk_fma_f32 v[228:229], v[4:5], v[238:239], v[228:229]
	v_pk_fma_f32 v[230:231], v[2:3], v[238:239], v[64:65]
	v_lshlrev_b32_e32 v240, 16, v88
	v_and_b32_e32 v241, 0xffff0000, v88
	v_pk_fma_f32 v[204:205], v[30:31], v[240:241], v[204:205]
	v_pk_fma_f32 v[206:207], v[28:29], v[240:241], v[206:207]
	v_pk_fma_f32 v[208:209], v[26:27], v[240:241], v[208:209]
	v_pk_fma_f32 v[210:211], v[24:25], v[240:241], v[210:211]
	v_pk_fma_f32 v[212:213], v[22:23], v[240:241], v[212:213]
	v_pk_fma_f32 v[214:215], v[20:21], v[240:241], v[214:215]
	v_pk_fma_f32 v[216:217], v[18:19], v[240:241], v[216:217]
	v_pk_fma_f32 v[218:219], v[16:17], v[240:241], v[218:219]
	v_pk_fma_f32 v[220:221], v[14:15], v[240:241], v[220:221]
	v_pk_fma_f32 v[222:223], v[12:13], v[240:241], v[222:223]
	v_pk_fma_f32 v[224:225], v[10:11], v[240:241], v[224:225]
	v_pk_fma_f32 v[226:227], v[8:9], v[240:241], v[226:227]
	v_pk_fma_f32 v[228:229], v[6:7], v[240:241], v[228:229]
	v_pk_fma_f32 v[230:231], v[4:5], v[240:241], v[230:231]
	v_pk_fma_f32 v[232:233], v[2:3], v[240:241], v[64:65]
	v_lshlrev_b32_e32 v236, 16, v89
	v_and_b32_e32 v237, 0xffff0000, v89
	v_pk_fma_f32 v[204:205], v[32:33], v[236:237], v[204:205]
	v_pk_fma_f32 v[206:207], v[30:31], v[236:237], v[206:207]
	v_pk_fma_f32 v[208:209], v[28:29], v[236:237], v[208:209]
	v_pk_fma_f32 v[210:211], v[26:27], v[236:237], v[210:211]
	v_pk_fma_f32 v[212:213], v[24:25], v[236:237], v[212:213]
	v_pk_fma_f32 v[214:215], v[22:23], v[236:237], v[214:215]
	v_pk_fma_f32 v[216:217], v[20:21], v[236:237], v[216:217]
	v_pk_fma_f32 v[218:219], v[18:19], v[236:237], v[218:219]
	v_pk_fma_f32 v[220:221], v[16:17], v[236:237], v[220:221]
	v_pk_fma_f32 v[222:223], v[14:15], v[236:237], v[222:223]
	v_pk_fma_f32 v[224:225], v[12:13], v[236:237], v[224:225]
	v_pk_fma_f32 v[226:227], v[10:11], v[236:237], v[226:227]
	v_pk_fma_f32 v[228:229], v[8:9], v[236:237], v[228:229]
	v_pk_fma_f32 v[230:231], v[6:7], v[236:237], v[230:231]
	v_pk_fma_f32 v[232:233], v[4:5], v[236:237], v[232:233]
	v_pk_fma_f32 v[234:235], v[2:3], v[236:237], v[64:65]
	v_lshlrev_b32_e32 v238, 16, v86
	v_and_b32_e32 v239, 0xffff0000, v86
	v_pk_fma_f32 v[204:205], v[34:35], v[238:239], v[204:205]
	v_pk_fma_f32 v[206:207], v[32:33], v[238:239], v[206:207]
	v_pk_fma_f32 v[208:209], v[30:31], v[238:239], v[208:209]
	v_pk_fma_f32 v[210:211], v[28:29], v[238:239], v[210:211]
	v_pk_fma_f32 v[212:213], v[26:27], v[238:239], v[212:213]
	v_pk_fma_f32 v[214:215], v[24:25], v[238:239], v[214:215]
	v_pk_fma_f32 v[216:217], v[22:23], v[238:239], v[216:217]
	v_pk_fma_f32 v[218:219], v[20:21], v[238:239], v[218:219]
	v_pk_fma_f32 v[220:221], v[18:19], v[238:239], v[220:221]
	v_pk_fma_f32 v[222:223], v[16:17], v[238:239], v[222:223]
	v_pk_fma_f32 v[224:225], v[14:15], v[238:239], v[224:225]
	v_pk_fma_f32 v[226:227], v[12:13], v[238:239], v[226:227]
	v_pk_fma_f32 v[228:229], v[10:11], v[238:239], v[228:229]
	v_pk_fma_f32 v[230:231], v[8:9], v[238:239], v[230:231]
	v_pk_fma_f32 v[232:233], v[6:7], v[238:239], v[232:233]
	v_pk_fma_f32 v[234:235], v[4:5], v[238:239], v[234:235]
	v_lshlrev_b32_e32 v240, 16, v87
	v_and_b32_e32 v241, 0xffff0000, v87
	v_pk_fma_f32 v[204:205], v[36:37], v[240:241], v[204:205]
	v_pk_fma_f32 v[206:207], v[34:35], v[240:241], v[206:207]
	v_pk_fma_f32 v[208:209], v[32:33], v[240:241], v[208:209]
	v_pk_fma_f32 v[210:211], v[30:31], v[240:241], v[210:211]
	v_pk_fma_f32 v[212:213], v[28:29], v[240:241], v[212:213]
	v_pk_fma_f32 v[214:215], v[26:27], v[240:241], v[214:215]
	v_pk_fma_f32 v[216:217], v[24:25], v[240:241], v[216:217]
	v_pk_fma_f32 v[218:219], v[22:23], v[240:241], v[218:219]
	v_pk_fma_f32 v[220:221], v[20:21], v[240:241], v[220:221]
	v_pk_fma_f32 v[222:223], v[18:19], v[240:241], v[222:223]
	v_pk_fma_f32 v[224:225], v[16:17], v[240:241], v[224:225]
	v_pk_fma_f32 v[226:227], v[14:15], v[240:241], v[226:227]
	v_pk_fma_f32 v[228:229], v[12:13], v[240:241], v[228:229]
	v_pk_fma_f32 v[230:231], v[10:11], v[240:241], v[230:231]
	v_pk_fma_f32 v[232:233], v[8:9], v[240:241], v[232:233]
	v_pk_fma_f32 v[234:235], v[6:7], v[240:241], v[234:235]
	v_lshlrev_b32_e32 v236, 16, v84
	v_and_b32_e32 v237, 0xffff0000, v84
	v_pk_fma_f32 v[204:205], v[38:39], v[236:237], v[204:205]
	v_pk_fma_f32 v[206:207], v[36:37], v[236:237], v[206:207]
	v_pk_fma_f32 v[208:209], v[34:35], v[236:237], v[208:209]
; __device__ __forceinline__ void p3_conv(const Ptrs& P, LAS unsigned char* lds, int first, int stride, int tid, int wave, int lane) {
;     ...
;         for (int r = 0; r < 46; ++r) {
;             const f32x2 u = (f32x2){bflo(uv[r]), bfhi(uv[r])};
; #pragma unroll
;             for (int t = 0; t < 16; ++t) { const int k = r - t; if (k >= 0 && k < CONV_W) a[t] += u * w[k]; }
;         }
	v_pk_fma_f32 v[210:211], v[32:33], v[236:237], v[210:211]
	v_pk_fma_f32 v[212:213], v[30:31], v[236:237], v[212:213]
	v_pk_fma_f32 v[214:215], v[28:29], v[236:237], v[214:215]
	v_pk_fma_f32 v[216:217], v[26:27], v[236:237], v[216:217]
	v_pk_fma_f32 v[218:219], v[24:25], v[236:237], v[218:219]
	v_pk_fma_f32 v[220:221], v[22:23], v[236:237], v[220:221]
	v_pk_fma_f32 v[222:223], v[20:21], v[236:237], v[222:223]
	v_pk_fma_f32 v[224:225], v[18:19], v[236:237], v[224:225]
	v_pk_fma_f32 v[226:227], v[16:17], v[236:237], v[226:227]
	v_pk_fma_f32 v[228:229], v[14:15], v[236:237], v[228:229]
	v_pk_fma_f32 v[230:231], v[12:13], v[236:237], v[230:231]
	v_pk_fma_f32 v[232:233], v[10:11], v[236:237], v[232:233]
	v_pk_fma_f32 v[234:235], v[8:9], v[236:237], v[234:235]
	v_lshlrev_b32_e32 v238, 16, v85
	v_and_b32_e32 v239, 0xffff0000, v85
	v_pk_fma_f32 v[204:205], v[40:41], v[238:239], v[204:205]
	v_pk_fma_f32 v[206:207], v[38:39], v[238:239], v[206:207]
	v_pk_fma_f32 v[208:209], v[36:37], v[238:239], v[208:209]
	v_pk_fma_f32 v[210:211], v[34:35], v[238:239], v[210:211]
	v_pk_fma_f32 v[212:213], v[32:33], v[238:239], v[212:213]
	v_pk_fma_f32 v[214:215], v[30:31], v[238:239], v[214:215]
	v_pk_fma_f32 v[216:217], v[28:29], v[238:239], v[216:217]
	v_pk_fma_f32 v[218:219], v[26:27], v[238:239], v[218:219]
	v_pk_fma_f32 v[220:221], v[24:25], v[238:239], v[220:221]
	v_pk_fma_f32 v[222:223], v[22:23], v[238:239], v[222:223]
	v_pk_fma_f32 v[224:225], v[20:21], v[238:239], v[224:225]
	v_pk_fma_f32 v[226:227], v[18:19], v[238:239], v[226:227]
	v_pk_fma_f32 v[228:229], v[16:17], v[238:239], v[228:229]
	v_pk_fma_f32 v[230:231], v[14:15], v[238:239], v[230:231]
	v_pk_fma_f32 v[232:233], v[12:13], v[238:239], v[232:233]
	v_pk_fma_f32 v[234:235], v[10:11], v[238:239], v[234:235]
	v_lshlrev_b32_e32 v240, 16, v82
	v_and_b32_e32 v241, 0xffff0000, v82
	v_pk_fma_f32 v[204:205], v[42:43], v[240:241], v[204:205]
	v_pk_fma_f32 v[206:207], v[40:41], v[240:241], v[206:207]
	v_pk_fma_f32 v[208:209], v[38:39], v[240:241], v[208:209]
	v_pk_fma_f32 v[210:211], v[36:37], v[240:241], v[210:211]
	v_pk_fma_f32 v[212:213], v[34:35], v[240:241], v[212:213]
	v_pk_fma_f32 v[214:215], v[32:33], v[240:241], v[214:215]
	v_pk_fma_f32 v[216:217], v[30:31], v[240:241], v[216:217]
	v_pk_fma_f32 v[218:219], v[28:29], v[240:241], v[218:219]
	v_pk_fma_f32 v[220:221], v[26:27], v[240:241], v[220:221]
	v_pk_fma_f32 v[222:223], v[24:25], v[240:241], v[222:223]
	v_pk_fma_f32 v[224:225], v[22:23], v[240:241], v[224:225]
	v_pk_fma_f32 v[226:227], v[20:21], v[240:241], v[226:227]
	v_pk_fma_f32 v[228:229], v[18:19], v[240:241], v[228:229]
	v_pk_fma_f32 v[230:231], v[16:17], v[240:241], v[230:231]
	v_pk_fma_f32 v[232:233], v[14:15], v[240:241], v[232:233]
	v_pk_fma_f32 v[234:235], v[12:13], v[240:241], v[234:235]
	v_lshlrev_b32_e32 v236, 16, v83
	v_and_b32_e32 v237, 0xffff0000, v83
	v_pk_fma_f32 v[204:205], v[44:45], v[236:237], v[204:205]
	v_pk_fma_f32 v[206:207], v[42:43], v[236:237], v[206:207]
	v_pk_fma_f32 v[208:209], v[40:41], v[236:237], v[208:209]
	v_pk_fma_f32 v[210:211], v[38:39], v[236:237], v[210:211]
	v_pk_fma_f32 v[212:213], v[36:37], v[236:237], v[212:213]
	v_pk_fma_f32 v[214:215], v[34:35], v[236:237], v[214:215]
	v_pk_fma_f32 v[216:217], v[32:33], v[236:237], v[216:217]
	v_pk_fma_f32 v[218:219], v[30:31], v[236:237], v[218:219]
	v_pk_fma_f32 v[220:221], v[28:29], v[236:237], v[220:221]
	v_pk_fma_f32 v[222:223], v[26:27], v[236:237], v[222:223]
	v_pk_fma_f32 v[224:225], v[24:25], v[236:237], v[224:225]
	v_pk_fma_f32 v[226:227], v[22:23], v[236:237], v[226:227]
	v_pk_fma_f32 v[228:229], v[20:21], v[236:237], v[228:229]
	v_pk_fma_f32 v[230:231], v[18:19], v[236:237], v[230:231]
	v_pk_fma_f32 v[232:233], v[16:17], v[236:237], v[232:233]
	v_pk_fma_f32 v[234:235], v[14:15], v[236:237], v[234:235]
	v_lshlrev_b32_e32 v238, 16, v80
	v_and_b32_e32 v239, 0xffff0000, v80
	v_pk_fma_f32 v[204:205], v[46:47], v[238:239], v[204:205]
	v_pk_fma_f32 v[206:207], v[44:45], v[238:239], v[206:207]
	v_pk_fma_f32 v[208:209], v[42:43], v[238:239], v[208:209]
	v_pk_fma_f32 v[210:211], v[40:41], v[238:239], v[210:211]
	v_pk_fma_f32 v[212:213], v[38:39], v[238:239], v[212:213]
	v_pk_fma_f32 v[214:215], v[36:37], v[238:239], v[214:215]
	v_pk_fma_f32 v[216:217], v[34:35], v[238:239], v[216:217]
	v_pk_fma_f32 v[218:219], v[32:33], v[238:239], v[218:219]
	v_pk_fma_f32 v[220:221], v[30:31], v[238:239], v[220:221]
	v_pk_fma_f32 v[222:223], v[28:29], v[238:239], v[222:223]
	v_pk_fma_f32 v[224:225], v[26:27], v[238:239], v[224:225]
	v_pk_fma_f32 v[226:227], v[24:25], v[238:239], v[226:227]
	v_pk_fma_f32 v[228:229], v[22:23], v[238:239], v[228:229]
	v_pk_fma_f32 v[230:231], v[20:21], v[238:239], v[230:231]
	v_pk_fma_f32 v[232:233], v[18:19], v[238:239], v[232:233]
	v_pk_fma_f32 v[234:235], v[16:17], v[238:239], v[234:235]
	v_lshlrev_b32_e32 v240, 16, v81
	v_and_b32_e32 v241, 0xffff0000, v81
	v_pk_fma_f32 v[204:205], v[48:49], v[240:241], v[204:205]
	v_pk_fma_f32 v[206:207], v[46:47], v[240:241], v[206:207]
	v_pk_fma_f32 v[208:209], v[44:45], v[240:241], v[208:209]
	v_pk_fma_f32 v[210:211], v[42:43], v[240:241], v[210:211]
	v_pk_fma_f32 v[212:213], v[40:41], v[240:241], v[212:213]
	v_pk_fma_f32 v[214:215], v[38:39], v[240:241], v[214:215]
	v_pk_fma_f32 v[216:217], v[36:37], v[240:241], v[216:217]
	v_pk_fma_f32 v[218:219], v[34:35], v[240:241], v[218:219]
	v_pk_fma_f32 v[220:221], v[32:33], v[240:241], v[220:221]
	v_pk_fma_f32 v[222:223], v[30:31], v[240:241], v[222:223]
	v_pk_fma_f32 v[224:225], v[28:29], v[240:241], v[224:225]
	v_pk_fma_f32 v[226:227], v[26:27], v[240:241], v[226:227]
	v_pk_fma_f32 v[228:229], v[24:25], v[240:241], v[228:229]
; __device__ __forceinline__ void p3_conv(const Ptrs& P, LAS unsigned char* lds, int first, int stride, int tid, int wave, int lane) {
;     ...
;         for (int r = 0; r < 46; ++r) {
;             const f32x2 u = (f32x2){bflo(uv[r]), bfhi(uv[r])};
; #pragma unroll
;             for (int t = 0; t < 16; ++t) { const int k = r - t; if (k >= 0 && k < CONV_W) a[t] += u * w[k]; }
;         }
	v_pk_fma_f32 v[230:231], v[22:23], v[240:241], v[230:231]
	v_pk_fma_f32 v[232:233], v[20:21], v[240:241], v[232:233]
	v_pk_fma_f32 v[234:235], v[18:19], v[240:241], v[234:235]
	v_lshlrev_b32_e32 v236, 16, v78
	v_and_b32_e32 v237, 0xffff0000, v78
	v_pk_fma_f32 v[204:205], v[50:51], v[236:237], v[204:205]
	v_pk_fma_f32 v[206:207], v[48:49], v[236:237], v[206:207]
	v_pk_fma_f32 v[208:209], v[46:47], v[236:237], v[208:209]
	v_pk_fma_f32 v[210:211], v[44:45], v[236:237], v[210:211]
	v_pk_fma_f32 v[212:213], v[42:43], v[236:237], v[212:213]
	v_pk_fma_f32 v[214:215], v[40:41], v[236:237], v[214:215]
	v_pk_fma_f32 v[216:217], v[38:39], v[236:237], v[216:217]
	v_pk_fma_f32 v[218:219], v[36:37], v[236:237], v[218:219]
	v_pk_fma_f32 v[220:221], v[34:35], v[236:237], v[220:221]
	v_pk_fma_f32 v[222:223], v[32:33], v[236:237], v[222:223]
	v_pk_fma_f32 v[224:225], v[30:31], v[236:237], v[224:225]
	v_pk_fma_f32 v[226:227], v[28:29], v[236:237], v[226:227]
	v_pk_fma_f32 v[228:229], v[26:27], v[236:237], v[228:229]
	v_pk_fma_f32 v[230:231], v[24:25], v[236:237], v[230:231]
	v_pk_fma_f32 v[232:233], v[22:23], v[236:237], v[232:233]
	v_pk_fma_f32 v[234:235], v[20:21], v[236:237], v[234:235]
	v_lshlrev_b32_e32 v238, 16, v79
	v_and_b32_e32 v239, 0xffff0000, v79
	v_pk_fma_f32 v[204:205], v[52:53], v[238:239], v[204:205]
	v_pk_fma_f32 v[206:207], v[50:51], v[238:239], v[206:207]
	v_pk_fma_f32 v[208:209], v[48:49], v[238:239], v[208:209]
	v_pk_fma_f32 v[210:211], v[46:47], v[238:239], v[210:211]
	v_pk_fma_f32 v[212:213], v[44:45], v[238:239], v[212:213]
	v_pk_fma_f32 v[214:215], v[42:43], v[238:239], v[214:215]
	v_pk_fma_f32 v[216:217], v[40:41], v[238:239], v[216:217]
	v_pk_fma_f32 v[218:219], v[38:39], v[238:239], v[218:219]
	v_pk_fma_f32 v[220:221], v[36:37], v[238:239], v[220:221]
	v_pk_fma_f32 v[222:223], v[34:35], v[238:239], v[222:223]
	v_pk_fma_f32 v[224:225], v[32:33], v[238:239], v[224:225]
	v_pk_fma_f32 v[226:227], v[30:31], v[238:239], v[226:227]
	v_pk_fma_f32 v[228:229], v[28:29], v[238:239], v[228:229]
	v_pk_fma_f32 v[230:231], v[26:27], v[238:239], v[230:231]
	v_pk_fma_f32 v[232:233], v[24:25], v[238:239], v[232:233]
	v_pk_fma_f32 v[234:235], v[22:23], v[238:239], v[234:235]
	v_lshlrev_b32_e32 v240, 16, v76
	v_and_b32_e32 v241, 0xffff0000, v76
	v_pk_fma_f32 v[204:205], v[54:55], v[240:241], v[204:205]
	v_pk_fma_f32 v[206:207], v[52:53], v[240:241], v[206:207]
	v_pk_fma_f32 v[208:209], v[50:51], v[240:241], v[208:209]
	v_pk_fma_f32 v[210:211], v[48:49], v[240:241], v[210:211]
	v_pk_fma_f32 v[212:213], v[46:47], v[240:241], v[212:213]
	v_pk_fma_f32 v[214:215], v[44:45], v[240:241], v[214:215]
	v_pk_fma_f32 v[216:217], v[42:43], v[240:241], v[216:217]
	v_pk_fma_f32 v[218:219], v[40:41], v[240:241], v[218:219]
	v_pk_fma_f32 v[220:221], v[38:39], v[240:241], v[220:221]
	v_pk_fma_f32 v[222:223], v[36:37], v[240:241], v[222:223]
	v_pk_fma_f32 v[224:225], v[34:35], v[240:241], v[224:225]
	v_pk_fma_f32 v[226:227], v[32:33], v[240:241], v[226:227]
	v_pk_fma_f32 v[228:229], v[30:31], v[240:241], v[228:229]
	v_pk_fma_f32 v[230:231], v[28:29], v[240:241], v[230:231]
	v_pk_fma_f32 v[232:233], v[26:27], v[240:241], v[232:233]
	v_pk_fma_f32 v[234:235], v[24:25], v[240:241], v[234:235]
	v_lshlrev_b32_e32 v236, 16, v77
	v_and_b32_e32 v237, 0xffff0000, v77
	v_pk_fma_f32 v[204:205], v[56:57], v[236:237], v[204:205]
	v_pk_fma_f32 v[206:207], v[54:55], v[236:237], v[206:207]
	v_pk_fma_f32 v[208:209], v[52:53], v[236:237], v[208:209]
	v_pk_fma_f32 v[210:211], v[50:51], v[236:237], v[210:211]
	v_pk_fma_f32 v[212:213], v[48:49], v[236:237], v[212:213]
	v_pk_fma_f32 v[214:215], v[46:47], v[236:237], v[214:215]
	v_pk_fma_f32 v[216:217], v[44:45], v[236:237], v[216:217]
	v_pk_fma_f32 v[218:219], v[42:43], v[236:237], v[218:219]
	v_pk_fma_f32 v[220:221], v[40:41], v[236:237], v[220:221]
	v_pk_fma_f32 v[222:223], v[38:39], v[236:237], v[222:223]
	v_pk_fma_f32 v[224:225], v[36:37], v[236:237], v[224:225]
	v_pk_fma_f32 v[226:227], v[34:35], v[236:237], v[226:227]
	v_pk_fma_f32 v[228:229], v[32:33], v[236:237], v[228:229]
	v_pk_fma_f32 v[230:231], v[30:31], v[236:237], v[230:231]
	v_pk_fma_f32 v[232:233], v[28:29], v[236:237], v[232:233]
	v_pk_fma_f32 v[234:235], v[26:27], v[236:237], v[234:235]
	v_lshlrev_b32_e32 v238, 16, v72
	v_and_b32_e32 v239, 0xffff0000, v72
	v_pk_fma_f32 v[204:205], v[58:59], v[238:239], v[204:205]
	v_pk_fma_f32 v[206:207], v[56:57], v[238:239], v[206:207]
	v_pk_fma_f32 v[208:209], v[54:55], v[238:239], v[208:209]
	v_pk_fma_f32 v[210:211], v[52:53], v[238:239], v[210:211]
	v_pk_fma_f32 v[212:213], v[50:51], v[238:239], v[212:213]
	v_pk_fma_f32 v[214:215], v[48:49], v[238:239], v[214:215]
	v_pk_fma_f32 v[216:217], v[46:47], v[238:239], v[216:217]
	v_pk_fma_f32 v[218:219], v[44:45], v[238:239], v[218:219]
	v_pk_fma_f32 v[220:221], v[42:43], v[238:239], v[220:221]
	v_pk_fma_f32 v[222:223], v[40:41], v[238:239], v[222:223]
	v_pk_fma_f32 v[224:225], v[38:39], v[238:239], v[224:225]
	v_pk_fma_f32 v[226:227], v[36:37], v[238:239], v[226:227]
	v_pk_fma_f32 v[228:229], v[34:35], v[238:239], v[228:229]
	v_pk_fma_f32 v[230:231], v[32:33], v[238:239], v[230:231]
	v_pk_fma_f32 v[232:233], v[30:31], v[238:239], v[232:233]
	v_pk_fma_f32 v[234:235], v[28:29], v[238:239], v[234:235]
	v_lshlrev_b32_e32 v240, 16, v73
	v_and_b32_e32 v241, 0xffff0000, v73
	v_pk_fma_f32 v[204:205], v[60:61], v[240:241], v[204:205]
	v_pk_fma_f32 v[206:207], v[58:59], v[240:241], v[206:207]
	v_pk_fma_f32 v[208:209], v[56:57], v[240:241], v[208:209]
	v_pk_fma_f32 v[210:211], v[54:55], v[240:241], v[210:211]
	v_pk_fma_f32 v[212:213], v[52:53], v[240:241], v[212:213]
; __device__ __forceinline__ void p3_conv(const Ptrs& P, LAS unsigned char* lds, int first, int stride, int tid, int wave, int lane) {
;     ...
;         for (int r = 0; r < 46; ++r) {
;             const f32x2 u = (f32x2){bflo(uv[r]), bfhi(uv[r])};
; #pragma unroll
;             for (int t = 0; t < 16; ++t) { const int k = r - t; if (k >= 0 && k < CONV_W) a[t] += u * w[k]; }
;         }
	v_pk_fma_f32 v[214:215], v[50:51], v[240:241], v[214:215]
	v_pk_fma_f32 v[216:217], v[48:49], v[240:241], v[216:217]
	v_pk_fma_f32 v[218:219], v[46:47], v[240:241], v[218:219]
	v_pk_fma_f32 v[220:221], v[44:45], v[240:241], v[220:221]
	v_pk_fma_f32 v[222:223], v[42:43], v[240:241], v[222:223]
	v_pk_fma_f32 v[224:225], v[40:41], v[240:241], v[224:225]
	v_pk_fma_f32 v[226:227], v[38:39], v[240:241], v[226:227]
	v_pk_fma_f32 v[228:229], v[36:37], v[240:241], v[228:229]
	v_pk_fma_f32 v[230:231], v[34:35], v[240:241], v[230:231]
	v_pk_fma_f32 v[232:233], v[32:33], v[240:241], v[232:233]
	v_pk_fma_f32 v[234:235], v[30:31], v[240:241], v[234:235]
	v_lshlrev_b32_e32 v236, 16, v74
	v_and_b32_e32 v237, 0xffff0000, v74
	v_pk_fma_f32 v[204:205], v[62:63], v[236:237], v[204:205]
	v_pk_fma_f32 v[206:207], v[60:61], v[236:237], v[206:207]
	v_pk_fma_f32 v[208:209], v[58:59], v[236:237], v[208:209]
	v_pk_fma_f32 v[210:211], v[56:57], v[236:237], v[210:211]
	v_pk_fma_f32 v[212:213], v[54:55], v[236:237], v[212:213]
	v_pk_fma_f32 v[214:215], v[52:53], v[236:237], v[214:215]
	v_pk_fma_f32 v[216:217], v[50:51], v[236:237], v[216:217]
	v_pk_fma_f32 v[218:219], v[48:49], v[236:237], v[218:219]
	v_pk_fma_f32 v[220:221], v[46:47], v[236:237], v[220:221]
	v_pk_fma_f32 v[222:223], v[44:45], v[236:237], v[222:223]
	v_pk_fma_f32 v[224:225], v[42:43], v[236:237], v[224:225]
	v_pk_fma_f32 v[226:227], v[40:41], v[236:237], v[226:227]
	v_pk_fma_f32 v[228:229], v[38:39], v[236:237], v[228:229]
	v_pk_fma_f32 v[230:231], v[36:37], v[236:237], v[230:231]
	v_pk_fma_f32 v[232:233], v[34:35], v[236:237], v[232:233]
	v_pk_fma_f32 v[234:235], v[32:33], v[236:237], v[234:235]
	v_lshlrev_b32_e32 v238, 16, v75
	v_and_b32_e32 v239, 0xffff0000, v75
	v_pk_fma_f32 v[206:207], v[62:63], v[238:239], v[206:207]
	v_pk_fma_f32 v[208:209], v[60:61], v[238:239], v[208:209]
	v_pk_fma_f32 v[210:211], v[58:59], v[238:239], v[210:211]
	v_pk_fma_f32 v[212:213], v[56:57], v[238:239], v[212:213]
	v_pk_fma_f32 v[214:215], v[54:55], v[238:239], v[214:215]
	v_pk_fma_f32 v[216:217], v[52:53], v[238:239], v[216:217]
	v_pk_fma_f32 v[218:219], v[50:51], v[238:239], v[218:219]
	v_pk_fma_f32 v[220:221], v[48:49], v[238:239], v[220:221]
	v_pk_fma_f32 v[222:223], v[46:47], v[238:239], v[222:223]
	v_pk_fma_f32 v[224:225], v[44:45], v[238:239], v[224:225]
	v_pk_fma_f32 v[226:227], v[42:43], v[238:239], v[226:227]
	v_pk_fma_f32 v[228:229], v[40:41], v[238:239], v[228:229]
	v_pk_fma_f32 v[230:231], v[38:39], v[238:239], v[230:231]
	v_pk_fma_f32 v[232:233], v[36:37], v[238:239], v[232:233]
	v_pk_fma_f32 v[234:235], v[34:35], v[238:239], v[234:235]
	v_lshlrev_b32_e32 v240, 16, v136
	v_and_b32_e32 v241, 0xffff0000, v136
	v_pk_fma_f32 v[208:209], v[62:63], v[240:241], v[208:209]
	v_pk_fma_f32 v[210:211], v[60:61], v[240:241], v[210:211]
	v_pk_fma_f32 v[212:213], v[58:59], v[240:241], v[212:213]
	v_pk_fma_f32 v[214:215], v[56:57], v[240:241], v[214:215]
	v_pk_fma_f32 v[216:217], v[54:55], v[240:241], v[216:217]
	v_pk_fma_f32 v[218:219], v[52:53], v[240:241], v[218:219]
	v_pk_fma_f32 v[220:221], v[50:51], v[240:241], v[220:221]
	v_pk_fma_f32 v[222:223], v[48:49], v[240:241], v[222:223]
	v_pk_fma_f32 v[224:225], v[46:47], v[240:241], v[224:225]
	v_pk_fma_f32 v[226:227], v[44:45], v[240:241], v[226:227]
	v_pk_fma_f32 v[228:229], v[42:43], v[240:241], v[228:229]
	v_pk_fma_f32 v[230:231], v[40:41], v[240:241], v[230:231]
	v_pk_fma_f32 v[232:233], v[38:39], v[240:241], v[232:233]
	v_pk_fma_f32 v[234:235], v[36:37], v[240:241], v[234:235]
	v_lshlrev_b32_e32 v236, 16, v142
	v_and_b32_e32 v237, 0xffff0000, v142
	v_pk_fma_f32 v[210:211], v[62:63], v[236:237], v[210:211]
	v_pk_fma_f32 v[212:213], v[60:61], v[236:237], v[212:213]
	v_pk_fma_f32 v[214:215], v[58:59], v[236:237], v[214:215]
	v_pk_fma_f32 v[216:217], v[56:57], v[236:237], v[216:217]
	v_pk_fma_f32 v[218:219], v[54:55], v[236:237], v[218:219]
	v_pk_fma_f32 v[220:221], v[52:53], v[236:237], v[220:221]
	v_pk_fma_f32 v[222:223], v[50:51], v[236:237], v[222:223]
	v_pk_fma_f32 v[224:225], v[48:49], v[236:237], v[224:225]
	v_pk_fma_f32 v[226:227], v[46:47], v[236:237], v[226:227]
	v_pk_fma_f32 v[228:229], v[44:45], v[236:237], v[228:229]
	v_pk_fma_f32 v[230:231], v[42:43], v[236:237], v[230:231]
	v_pk_fma_f32 v[232:233], v[40:41], v[236:237], v[232:233]
	v_pk_fma_f32 v[234:235], v[38:39], v[236:237], v[234:235]
	v_lshlrev_b32_e32 v238, 16, v144
	v_and_b32_e32 v239, 0xffff0000, v144
	v_pk_fma_f32 v[212:213], v[62:63], v[238:239], v[212:213]
	v_pk_fma_f32 v[214:215], v[60:61], v[238:239], v[214:215]
	v_pk_fma_f32 v[216:217], v[58:59], v[238:239], v[216:217]
	v_pk_fma_f32 v[218:219], v[56:57], v[238:239], v[218:219]
	v_pk_fma_f32 v[220:221], v[54:55], v[238:239], v[220:221]
	v_pk_fma_f32 v[222:223], v[52:53], v[238:239], v[222:223]
	v_pk_fma_f32 v[224:225], v[50:51], v[238:239], v[224:225]
	v_pk_fma_f32 v[226:227], v[48:49], v[238:239], v[226:227]
	v_pk_fma_f32 v[228:229], v[46:47], v[238:239], v[228:229]
	v_pk_fma_f32 v[230:231], v[44:45], v[238:239], v[230:231]
	v_pk_fma_f32 v[232:233], v[42:43], v[238:239], v[232:233]
	v_pk_fma_f32 v[234:235], v[40:41], v[238:239], v[234:235]
	v_lshlrev_b32_e32 v240, 16, v146
	v_and_b32_e32 v241, 0xffff0000, v146
	v_pk_fma_f32 v[214:215], v[62:63], v[240:241], v[214:215]
	v_pk_fma_f32 v[216:217], v[60:61], v[240:241], v[216:217]
	v_pk_fma_f32 v[218:219], v[58:59], v[240:241], v[218:219]
	v_pk_fma_f32 v[220:221], v[56:57], v[240:241], v[220:221]
	v_pk_fma_f32 v[222:223], v[54:55], v[240:241], v[222:223]
	v_pk_fma_f32 v[224:225], v[52:53], v[240:241], v[224:225]
	v_pk_fma_f32 v[226:227], v[50:51], v[240:241], v[226:227]
; __device__ __forceinline__ void p3_conv(const Ptrs& P, LAS unsigned char* lds, int first, int stride, int tid, int wave, int lane) {
;     ...
;         for (int r = 0; r < 46; ++r) {
;             const f32x2 u = (f32x2){bflo(uv[r]), bfhi(uv[r])};
; #pragma unroll
;             for (int t = 0; t < 16; ++t) { const int k = r - t; if (k >= 0 && k < CONV_W) a[t] += u * w[k]; }
;         }
; #pragma unroll
;         for (int t = 0; t < 16; ++t) {
;             float s1 = a[t].x + a[t].y, s2 = a[t].x * a[t].x + a[t].y * a[t].y;
	v_pk_fma_f32 v[228:229], v[48:49], v[240:241], v[228:229]
	v_pk_fma_f32 v[230:231], v[46:47], v[240:241], v[230:231]
	v_pk_fma_f32 v[232:233], v[44:45], v[240:241], v[232:233]
	v_pk_fma_f32 v[234:235], v[42:43], v[240:241], v[234:235]
	v_lshlrev_b32_e32 v236, 16, v148
	v_and_b32_e32 v237, 0xffff0000, v148
	v_pk_fma_f32 v[216:217], v[62:63], v[236:237], v[216:217]
	v_pk_fma_f32 v[218:219], v[60:61], v[236:237], v[218:219]
	v_pk_fma_f32 v[220:221], v[58:59], v[236:237], v[220:221]
	v_pk_fma_f32 v[222:223], v[56:57], v[236:237], v[222:223]
	v_pk_fma_f32 v[224:225], v[54:55], v[236:237], v[224:225]
	v_pk_fma_f32 v[226:227], v[52:53], v[236:237], v[226:227]
	v_pk_fma_f32 v[228:229], v[50:51], v[236:237], v[228:229]
	v_pk_fma_f32 v[230:231], v[48:49], v[236:237], v[230:231]
	v_pk_fma_f32 v[232:233], v[46:47], v[236:237], v[232:233]
	v_pk_fma_f32 v[234:235], v[44:45], v[236:237], v[234:235]
	v_lshlrev_b32_e32 v238, 16, v150
	v_and_b32_e32 v239, 0xffff0000, v150
	v_pk_fma_f32 v[218:219], v[62:63], v[238:239], v[218:219]
	v_pk_fma_f32 v[220:221], v[60:61], v[238:239], v[220:221]
	v_pk_fma_f32 v[222:223], v[58:59], v[238:239], v[222:223]
	v_pk_fma_f32 v[224:225], v[56:57], v[238:239], v[224:225]
	v_pk_fma_f32 v[226:227], v[54:55], v[238:239], v[226:227]
	v_pk_fma_f32 v[228:229], v[52:53], v[238:239], v[228:229]
	v_pk_fma_f32 v[230:231], v[50:51], v[238:239], v[230:231]
	v_pk_fma_f32 v[232:233], v[48:49], v[238:239], v[232:233]
	v_pk_fma_f32 v[234:235], v[46:47], v[238:239], v[234:235]
	v_lshlrev_b32_e32 v240, 16, v152
	v_and_b32_e32 v241, 0xffff0000, v152
	v_pk_fma_f32 v[220:221], v[62:63], v[240:241], v[220:221]
	v_pk_fma_f32 v[222:223], v[60:61], v[240:241], v[222:223]
	v_pk_fma_f32 v[224:225], v[58:59], v[240:241], v[224:225]
	v_pk_fma_f32 v[226:227], v[56:57], v[240:241], v[226:227]
	v_pk_fma_f32 v[228:229], v[54:55], v[240:241], v[228:229]
	v_pk_fma_f32 v[230:231], v[52:53], v[240:241], v[230:231]
	v_pk_fma_f32 v[232:233], v[50:51], v[240:241], v[232:233]
	v_pk_fma_f32 v[234:235], v[48:49], v[240:241], v[234:235]
	v_lshlrev_b32_e32 v236, 16, v154
	v_and_b32_e32 v237, 0xffff0000, v154
	v_pk_fma_f32 v[222:223], v[62:63], v[236:237], v[222:223]
	v_pk_fma_f32 v[224:225], v[60:61], v[236:237], v[224:225]
	v_pk_fma_f32 v[226:227], v[58:59], v[236:237], v[226:227]
	v_pk_fma_f32 v[228:229], v[56:57], v[236:237], v[228:229]
	v_pk_fma_f32 v[230:231], v[54:55], v[236:237], v[230:231]
	v_pk_fma_f32 v[232:233], v[52:53], v[236:237], v[232:233]
	v_pk_fma_f32 v[234:235], v[50:51], v[236:237], v[234:235]
	v_lshlrev_b32_e32 v238, 16, v156
	v_and_b32_e32 v239, 0xffff0000, v156
	v_pk_fma_f32 v[224:225], v[62:63], v[238:239], v[224:225]
	v_pk_fma_f32 v[226:227], v[60:61], v[238:239], v[226:227]
	v_pk_fma_f32 v[228:229], v[58:59], v[238:239], v[228:229]
	v_pk_fma_f32 v[230:231], v[56:57], v[238:239], v[230:231]
	v_pk_fma_f32 v[232:233], v[54:55], v[238:239], v[232:233]
	v_pk_fma_f32 v[234:235], v[52:53], v[238:239], v[234:235]
	v_lshlrev_b32_e32 v240, 16, v158
	v_and_b32_e32 v241, 0xffff0000, v158
	v_pk_fma_f32 v[226:227], v[62:63], v[240:241], v[226:227]
	v_pk_fma_f32 v[228:229], v[60:61], v[240:241], v[228:229]
	v_pk_fma_f32 v[230:231], v[58:59], v[240:241], v[230:231]
	v_pk_fma_f32 v[232:233], v[56:57], v[240:241], v[232:233]
	v_pk_fma_f32 v[234:235], v[54:55], v[240:241], v[234:235]
	v_lshlrev_b32_e32 v236, 16, v160
	v_and_b32_e32 v237, 0xffff0000, v160
	v_pk_fma_f32 v[228:229], v[62:63], v[236:237], v[228:229]
	v_pk_fma_f32 v[230:231], v[60:61], v[236:237], v[230:231]
	v_pk_fma_f32 v[232:233], v[58:59], v[236:237], v[232:233]
	v_pk_fma_f32 v[234:235], v[56:57], v[236:237], v[234:235]
	v_lshlrev_b32_e32 v238, 16, v162
	v_and_b32_e32 v239, 0xffff0000, v162
	v_pk_fma_f32 v[230:231], v[62:63], v[238:239], v[230:231]
	v_pk_fma_f32 v[232:233], v[60:61], v[238:239], v[232:233]
	v_pk_fma_f32 v[234:235], v[58:59], v[238:239], v[234:235]
	v_lshlrev_b32_e32 v240, 16, v164
	v_and_b32_e32 v241, 0xffff0000, v164
	v_pk_fma_f32 v[232:233], v[62:63], v[240:241], v[232:233]
	v_pk_fma_f32 v[234:235], v[60:61], v[240:241], v[234:235]
	v_lshlrev_b32_e32 v236, 16, v201
	v_and_b32_e32 v237, 0xffff0000, v201
	v_pk_fma_f32 v[234:235], v[62:63], v[236:237], v[234:235]
	v_pk_mul_f32 v[72:73], v[204:205], v[204:205]
	v_pk_mul_f32 v[74:75], v[206:207], v[206:207]
	v_pk_mul_f32 v[76:77], v[208:209], v[208:209]
	v_pk_mul_f32 v[78:79], v[210:211], v[210:211]
	v_pk_mul_f32 v[80:81], v[212:213], v[212:213]
	v_pk_mul_f32 v[82:83], v[214:215], v[214:215]
	v_pk_mul_f32 v[84:85], v[216:217], v[216:217]
	v_pk_mul_f32 v[86:87], v[218:219], v[218:219]
	v_pk_mul_f32 v[88:89], v[220:221], v[220:221]
	v_pk_mul_f32 v[90:91], v[222:223], v[222:223]
	v_pk_mul_f32 v[92:93], v[224:225], v[224:225]
	v_pk_mul_f32 v[94:95], v[226:227], v[226:227]
	v_pk_mul_f32 v[96:97], v[228:229], v[228:229]
	v_pk_mul_f32 v[98:99], v[230:231], v[230:231]
	v_pk_mul_f32 v[100:101], v[232:233], v[232:233]
	v_pk_mul_f32 v[102:103], v[234:235], v[234:235]
	v_add_f32_e32 v104, v204, v205
	v_add_f32_e32 v106, v206, v207
	v_add_f32_e32 v108, v208, v209
	v_add_f32_e32 v110, v210, v211
	v_add_f32_e32 v112, v212, v213
	v_add_f32_e32 v114, v214, v215
	v_add_f32_e32 v116, v216, v217
	v_add_f32_e32 v118, v218, v219
	v_add_f32_e32 v120, v220, v221
	v_add_f32_e32 v122, v222, v223
	v_add_f32_e32 v124, v224, v225
; __device__ __forceinline__ void p3_conv(const Ptrs& P, LAS unsigned char* lds, int first, int stride, int tid, int wave, int lane) {
;     ...
;         for (int t = 0; t < 16; ++t) {
;             float s1 = a[t].x + a[t].y, s2 = a[t].x * a[t].x + a[t].y * a[t].y;
; #pragma unroll
;             for (int k = 0; k < 6; ++k) {
;                 s1 += __builtin_bit_cast(float, __builtin_amdgcn_ds_bpermute(bpi[k], __builtin_bit_cast(int, s1)));
;                 s2 += __builtin_bit_cast(float, __builtin_amdgcn_ds_bpermute(bpi[k], __builtin_bit_cast(int, s2)));
;             }
;             if (lane == 0) { red[(wave * 16 + t) * 2] = s1; red[(wave * 16 + t) * 2 + 1] = s2; }
;         }
	v_add_f32_e32 v126, v226, v227
	v_add_f32_e32 v128, v228, v229
	v_add_f32_e32 v130, v230, v231
	v_add_f32_e32 v132, v232, v233
	v_add_f32_e32 v134, v234, v235
	v_add_f32_e32 v105, v72, v73
	v_add_f32_e32 v107, v74, v75
	v_add_f32_e32 v109, v76, v77
	v_add_f32_e32 v111, v78, v79
	v_add_f32_e32 v113, v80, v81
	v_add_f32_e32 v115, v82, v83
	v_add_f32_e32 v117, v84, v85
	v_add_f32_e32 v119, v86, v87
	v_add_f32_e32 v121, v88, v89
	v_add_f32_e32 v123, v90, v91
	v_add_f32_e32 v125, v92, v93
	v_add_f32_e32 v127, v94, v95
	v_add_f32_e32 v129, v96, v97
	v_add_f32_e32 v131, v98, v99
	v_add_f32_e32 v133, v100, v101
	v_add_f32_e32 v135, v102, v103
	v_permlane32_swap_b32_e32 v104, v105
	v_permlane32_swap_b32_e32 v106, v107
	v_permlane32_swap_b32_e32 v108, v109
	v_permlane32_swap_b32_e32 v110, v111
	v_permlane32_swap_b32_e32 v112, v113
	v_permlane32_swap_b32_e32 v114, v115
	v_permlane32_swap_b32_e32 v116, v117
	v_permlane32_swap_b32_e32 v118, v119
	v_permlane32_swap_b32_e32 v120, v121
	v_permlane32_swap_b32_e32 v122, v123
	v_permlane32_swap_b32_e32 v124, v125
	v_permlane32_swap_b32_e32 v126, v127
	v_permlane32_swap_b32_e32 v128, v129
	v_permlane32_swap_b32_e32 v130, v131
	v_permlane32_swap_b32_e32 v132, v133
	v_permlane32_swap_b32_e32 v134, v135
	v_add_f32_e32 v104, v104, v105
	v_add_f32_e32 v106, v106, v107
	v_add_f32_e32 v108, v108, v109
	v_add_f32_e32 v110, v110, v111
	v_add_f32_e32 v112, v112, v113
	v_add_f32_e32 v114, v114, v115
	v_add_f32_e32 v116, v116, v117
	v_add_f32_e32 v118, v118, v119
	v_add_f32_e32 v120, v120, v121
	v_add_f32_e32 v122, v122, v123
	v_add_f32_e32 v124, v124, v125
	v_add_f32_e32 v126, v126, v127
	v_add_f32_e32 v128, v128, v129
	v_add_f32_e32 v130, v130, v131
	v_add_f32_e32 v132, v132, v133
	v_add_f32_e32 v134, v134, v135
	v_permlane16_swap_b32_e32 v104, v106
	v_permlane16_swap_b32_e32 v108, v110
	v_permlane16_swap_b32_e32 v112, v114
	v_permlane16_swap_b32_e32 v116, v118
	v_permlane16_swap_b32_e32 v120, v122
	v_permlane16_swap_b32_e32 v124, v126
	v_permlane16_swap_b32_e32 v128, v130
	v_permlane16_swap_b32_e32 v132, v134
	v_add_f32_e32 v104, v104, v106
	v_add_f32_e32 v108, v108, v110
	v_add_f32_e32 v112, v112, v114
	v_add_f32_e32 v116, v116, v118
	v_add_f32_e32 v120, v120, v122
	v_add_f32_e32 v124, v124, v126
	v_add_f32_e32 v128, v128, v130
	v_add_f32_e32 v132, v132, v134
	v_add_f32_dpp v104, v104, v104 quad_perm:[1,0,3,2] row_mask:0xf bank_mask:0xf
	v_add_f32_dpp v108, v108, v108 quad_perm:[1,0,3,2] row_mask:0xf bank_mask:0xf
	v_add_f32_dpp v112, v112, v112 quad_perm:[1,0,3,2] row_mask:0xf bank_mask:0xf
	v_add_f32_dpp v116, v116, v116 quad_perm:[1,0,3,2] row_mask:0xf bank_mask:0xf
	v_add_f32_dpp v120, v120, v120 quad_perm:[1,0,3,2] row_mask:0xf bank_mask:0xf
	v_add_f32_dpp v124, v124, v124 quad_perm:[1,0,3,2] row_mask:0xf bank_mask:0xf
	v_add_f32_dpp v128, v128, v128 quad_perm:[1,0,3,2] row_mask:0xf bank_mask:0xf
	v_add_f32_dpp v132, v132, v132 quad_perm:[1,0,3,2] row_mask:0xf bank_mask:0xf
	v_add_f32_dpp v104, v104, v104 quad_perm:[2,3,0,1] row_mask:0xf bank_mask:0xf
	v_add_f32_dpp v108, v108, v108 quad_perm:[2,3,0,1] row_mask:0xf bank_mask:0xf
	v_add_f32_dpp v112, v112, v112 quad_perm:[2,3,0,1] row_mask:0xf bank_mask:0xf
	v_add_f32_dpp v116, v116, v116 quad_perm:[2,3,0,1] row_mask:0xf bank_mask:0xf
	v_add_f32_dpp v120, v120, v120 quad_perm:[2,3,0,1] row_mask:0xf bank_mask:0xf
	v_add_f32_dpp v124, v124, v124 quad_perm:[2,3,0,1] row_mask:0xf bank_mask:0xf
	v_add_f32_dpp v128, v128, v128 quad_perm:[2,3,0,1] row_mask:0xf bank_mask:0xf
	v_add_f32_dpp v132, v132, v132 quad_perm:[2,3,0,1] row_mask:0xf bank_mask:0xf
	v_add_f32_dpp v104, v104, v104 row_half_mirror row_mask:0xf bank_mask:0xf
	v_add_f32_dpp v108, v108, v108 row_half_mirror row_mask:0xf bank_mask:0xf
	v_add_f32_dpp v112, v112, v112 row_half_mirror row_mask:0xf bank_mask:0xf
	v_add_f32_dpp v116, v116, v116 row_half_mirror row_mask:0xf bank_mask:0xf
	v_add_f32_dpp v120, v120, v120 row_half_mirror row_mask:0xf bank_mask:0xf
	v_add_f32_dpp v124, v124, v124 row_half_mirror row_mask:0xf bank_mask:0xf
	v_add_f32_dpp v128, v128, v128 row_half_mirror row_mask:0xf bank_mask:0xf
	v_add_f32_dpp v132, v132, v132 row_half_mirror row_mask:0xf bank_mask:0xf
	v_add_f32_dpp v104, v104, v104 row_mirror row_mask:0xf bank_mask:0xf
	v_add_f32_dpp v108, v108, v108 row_mirror row_mask:0xf bank_mask:0xf
	v_add_f32_dpp v112, v112, v112 row_mirror row_mask:0xf bank_mask:0xf
	v_add_f32_dpp v116, v116, v116 row_mirror row_mask:0xf bank_mask:0xf
	v_add_f32_dpp v120, v120, v120 row_mirror row_mask:0xf bank_mask:0xf
	v_add_f32_dpp v124, v124, v124 row_mirror row_mask:0xf bank_mask:0xf
	v_add_f32_dpp v128, v128, v128 row_mirror row_mask:0xf bank_mask:0xf
	v_add_f32_dpp v132, v132, v132 row_mirror row_mask:0xf bank_mask:0xf
	v_lshrrev_b32_e32 v244, 4, v1
	v_and_b32_e32 v245, 1, v244
	v_lshlrev_b32_e32 v245, 1, v245
	v_lshrrev_b32_e32 v244, 1, v244
	v_or_b32_e32 v244, v244, v245
	v_lshl_add_u32 v244, v244, 2, s37
	s_mov_b64 s[0:1], exec
	s_mov_b32 exec_lo, 0x10001
	s_mov_b32 exec_hi, 0x10001
	ds_write_b32 v244, v104
	ds_write_b32 v244, v108 offset:16
	ds_write_b32 v244, v112 offset:32
	ds_write_b32 v244, v116 offset:48
	ds_write_b32 v244, v120 offset:64
	ds_write_b32 v244, v124 offset:80
	ds_write_b32 v244, v128 offset:96
	ds_write_b32 v244, v132 offset:112
	s_mov_b64 exec, s[0:1]
